# speedup vs baseline: 1.0287x; 1.0078x over previous
; __device__ __forceinline__ int otid() { int t = threadIdx.x; asm volatile("" : "+v"(t)); return t; }
; __device__ void attn_b_item(const Params& p, int layer, int b, int h, int qblk, unsigned char* smem) {
;     const int tid_ = otid(); const int lane = tid_ & 63, w = tid_ >> 6, l15 = lane & 15, kg = lane >> 4;
;     const bf16_t* proj = reinterpret_cast<const bf16_t*>(p.ws + WS_PROJ) + (size_t)b * SEQ * PW;
;     const bf16_t* kbase = proj + 768 + h * 64;
;     const bf16_t* vbase = reinterpret_cast<const bf16_t*>(p.ws + WS_VT) + ((size_t)b * VTW + 256 + h * 64) * SEQ;
;     const int fo = swz(l15 * 64 + kg * 16);
;     const TileOfs tofs = make_tile_ofs(tid_);
;     const int qw0 = qblk * 256 + w * 32;
;     bf16x8 qf[2][2];
; #pragma unroll
;     for (int c = 0; c < 2; ++c)
; #pragma unroll
;         for (int qt = 0; qt < 2; ++qt)
;             qf[c][qt] = *reinterpret_cast<const bf16x8*>(proj + (size_t)(qw0 + qt * 16 + l15) * PW + 512 + h * 64 + c * 32 + kg * 8);
;     f32x4 o[2][4];
;     float R[2] = {0.f, 0.f};
; #pragma unroll
;     for (int qt = 0; qt < 2; ++qt)
; #pragma unroll
;         for (int et = 0; et < 4; ++et) o[qt][et] = f32x4{0.f, 0.f, 0.f, 0.f};
;     const float c2 = 0.125f * LOG2E;
;     const int gmax = qblk * 8 + w;
;     const int jmax = qblk * 4 + 3;
;     const float RSTOP = -110.f * LOG2E;
;     TileRegs tr;
;     attn_tile_load(tr, kbase, vbase, jmax * 64, tofs);
;     attn_tile_store(tr, smem, tofs);
;     __syncthreads();
.LBB0_409:
	s_and_b64 vcc, exec, s[2:3]
	s_cbranch_vccz .LBB0_430
	v_readfirstlane_b32 s100, v189
	s_lshr_b32 s100, s100, 7
	s_sub_i32 s100, 3, s100
	s_bfe_u32 s30, s28, 0x10002
	s_add_i32 s8, s28, 0xfffffc00
	s_mul_i32 s2, s30, 0x3400000
	s_add_u32 s4, s42, s2
	s_addc_u32 s5, s43, 0
	s_lshl_b32 s2, s28, 6
	s_and_b32 s29, s2, 0xc0
	s_mul_i32 s2, s30, 0x280
	s_add_i32 s2, s2, s29
	v_mov_b32_e32 v0, v189
	s_lshl_b32 s2, s2, 15
	s_add_i32 s2, s2, 0x800000
	v_lshrrev_b32_e32 v20, 3, v0
	s_add_u32 s2, s52, s2
	v_and_b32_e32 v2, 6, v20
	v_lshrrev_b32_e32 v3, 2, v0
	v_ashrrev_i32_e32 v18, 6, v0
	s_addc_u32 s3, s53, 0
	v_and_or_b32 v21, v3, 1, v2
	v_lshrrev_b32_e32 v2, 1, v0
	s_lshl_b32 s6, s8, 5
	v_and_b32_e32 v23, 4, v2
	v_and_b32_e32 v24, 3, v0
	s_and_b32 s6, s6, 0xffffff00
	v_lshlrev_b32_e32 v25, 5, v18
	v_and_b32_e32 v117, 15, v0
	v_or_b32_e32 v2, v23, v24
	v_add_u32_e32 v94, s6, v25
	v_lshlrev_b32_e32 v6, 3, v2
	v_or_b32_e32 v7, v94, v117
	v_mov_b64_e32 v[2:3], s[4:5]
	s_waitcnt lgkmcnt(0)
	v_mad_i64_i32 v[4:5], s[6:7], v7, s48, v[2:3]
	s_lshl_b32 s62, s29, 1
	v_lshl_add_u64 v[10:11], v[4:5], 0, s[62:63]
	v_or_b32_e32 v4, 16, v7
	v_ashrrev_i32_e32 v19, 3, v0
	v_mad_i64_i32 v[2:3], s[6:7], v4, s48, v[2:3]
	s_add_u32 s4, s4, s62
	v_and_or_b32 v22, v19, -8, v21
	s_addc_u32 s5, s5, 0
	s_lshr_b32 s6, s8, 1
	v_lshl_add_u64 v[12:13], v[2:3], 0, s[62:63]
	v_mul_lo_u32 v2, v22, s82
	s_and_b32 s9, s8, -8
	s_or_b32 s8, s6, 3
	v_or_b32_e32 v2, v2, v6
	s_lshl_b32 s62, s8, 6
	s_mul_i32 s6, s8, 0x34000
	s_mul_hi_u32 s7, s62, 0xd00
	s_add_u32 s6, s4, s6
	v_ashrrev_i32_e32 v3, 31, v2
	s_addc_u32 s7, s5, s7
	v_lshlrev_b64 v[14:15], 1, v[2:3]
	v_lshl_or_b32 v6, v22, 14, v6
	v_lshl_add_u64 v[2:3], s[6:7], 0, v[14:15]
	s_lshl_b64 s[6:7], s[62:63], 1
	s_add_u32 s6, s2, s6
	v_ashrrev_i32_e32 v7, 31, v6
	v_bfe_u32 v116, v0, 4, 2
	s_addc_u32 s7, s3, s7
	v_lshlrev_b64 v[16:17], 1, v[6:7]
	v_lshlrev_b32_e32 v92, 4, v116
	v_mov_b32_e32 v93, v1
	global_load_dwordx4 v[2:5], v[2:3], off offset:1536
	v_lshl_add_u64 v[6:7], s[6:7], 0, v[16:17]
	v_lshl_add_u64 v[10:11], v[10:11], 0, v[92:93]
	global_load_dwordx4 v[6:9], v[6:7], off
	v_lshl_add_u64 v[12:13], v[12:13], 0, v[92:93]
	global_load_dwordx4 v[36:39], v[10:11], off offset:1024
	global_load_dwordx4 v[40:43], v[10:11], off offset:1088
	global_load_dwordx4 v[44:47], v[12:13], off offset:1024
	global_load_dwordx4 v[48:51], v[12:13], off offset:1088
	v_lshrrev_b32_e32 v11, 1, v19
	v_and_b32_e32 v11, 12, v11
	v_and_or_b32 v11, v21, 3, v11
	v_lshlrev_b32_e32 v13, 8, v23
	v_lshlrev_b32_e32 v23, 1, v19
	v_lshlrev_b32_e32 v10, 2, v0
	v_lshrrev_b32_e32 v12, 7, v0
	v_lshlrev_b32_e32 v11, 6, v11
	v_lshlrev_b32_e32 v21, 4, v24
	v_and_b32_e32 v23, 32, v23
	v_bfe_u32 v0, v0, 5, 1
	v_bitop3_b32 v11, v11, v23, v21 bitop3:0x36
	v_and_b32_e32 v23, 0x3ffffe, v18
	v_and_or_b32 v0, v12, s94, v0
	v_and_or_b32 v20, v20, 1, v23
	v_lshlrev_b32_e32 v22, 6, v22
	v_lshlrev_b32_e32 v19, 2, v19
	v_lshlrev_b32_e32 v0, 11, v0
	v_and_b32_e32 v10, 32, v10
	v_lshlrev_b32_e32 v20, 10, v20
	v_and_or_b32 v21, v22, s64, v21
	v_and_b32_e32 v19, 32, v19
	v_lshlrev_b32_e32 v96, 3, v116
	v_lshl_or_b32 v22, v117, 6, v92
	v_or3_b32 v93, v0, v13, v11
	v_lshl_add_u64 v[100:101], s[2:3], 0, v[16:17]
	s_movk_i32 s2, 0x2400
	v_or_b32_e32 v0, v25, v117
	v_bitop3_b32 v97, v19, v20, v21 bitop3:0xde
	v_bitop3_b32 v118, v22, s2, v10 bitop3:0xde
	s_movk_i32 s2, 0x1000
	v_sub_u32_e32 v0, v0, v96
	v_add_u32_e32 v95, s9, v18
	v_lshl_add_u64 v[98:99], s[4:5], 0, v[14:15]
	v_bitop3_b32 v119, v22, s2, v10 bitop3:0xde
	v_add_u32_e32 v120, 0xffffff20, v0
	v_lshl_add_u32 v120, s100, 6, v120
	v_add_u32_e32 v121, -7, v18
	v_mov_b32_e32 v0, v1
	s_or_b32 s31, s9, 7
	s_mov_b32 s34, 0
	v_mov_b32_e32 v122, 0
	s_mov_b64 s[22:23], 0
	v_mov_b32_e32 v124, s8
	v_mov_b32_e32 v123, 0
	s_sub_i32 s2, s8, 1
	s_lshl_b32 s2, s2, 6
	s_mul_i32 s6, s2, 0xd00
	s_mul_hi_u32 s7, s2, 0xd00
	v_lshl_add_u64 v[84:85], v[98:99], 0, s[6:7]
	global_load_dwordx4 v[60:63], v[84:85], off offset:1536
	s_lshl_b32 s6, s2, 1
	s_mov_b32 s7, 0
	v_lshl_add_u64 v[84:85], v[100:101], 0, s[6:7]
	global_load_dwordx4 v[64:67], v[84:85], off
	s_sub_i32 s2, s8, 2
	s_lshl_b32 s2, s2, 6
	s_mul_i32 s6, s2, 0xd00
	s_mul_hi_u32 s7, s2, 0xd00
	v_lshl_add_u64 v[84:85], v[98:99], 0, s[6:7]
	global_load_dwordx4 v[68:71], v[84:85], off offset:1536
	s_lshl_b32 s6, s2, 1
	s_mov_b32 s7, 0
	v_lshl_add_u64 v[84:85], v[100:101], 0, s[6:7]
	global_load_dwordx4 v[72:75], v[84:85], off
	s_sub_i32 s2, s8, 3
	s_lshl_b32 s2, s2, 6
	s_mul_i32 s6, s2, 0xd00
	s_mul_hi_u32 s7, s2, 0xd00
	v_lshl_add_u64 v[84:85], v[98:99], 0, s[6:7]
	global_load_dwordx4 v[76:79], v[84:85], off offset:1536
	s_lshl_b32 s6, s2, 1
	s_mov_b32 s7, 0
	v_lshl_add_u64 v[84:85], v[100:101], 0, s[6:7]
	global_load_dwordx4 v[80:83], v[84:85], off
	s_and_b32 s2, s8, 7
	s_lshl_b32 s2, s2, 14
	v_add_u32_e32 v84, s2, v93
	v_add_u32_e32 v85, s2, v97
	s_waitcnt vmcnt(11)
	ds_write_b128 v84, v[2:5]
	v_mov_b32_e32 v2, v1
	v_mov_b32_e32 v3, v1
	s_waitcnt vmcnt(10)
	ds_write_b128 v85, v[6:9] offset:8192
	s_sub_i32 s2, s8, 1
	s_and_b32 s2, s2, 7
	s_lshl_b32 s2, s2, 14
	v_add_u32_e32 v84, s2, v93
	v_add_u32_e32 v85, s2, v97
	s_waitcnt vmcnt(5)
	ds_write_b128 v84, v[60:63]
	s_waitcnt vmcnt(4)
	ds_write_b128 v85, v[64:67] offset:8192
	s_sub_i32 s2, s8, 2
	s_and_b32 s2, s2, 7
	s_lshl_b32 s2, s2, 14
	v_add_u32_e32 v84, s2, v93
	v_add_u32_e32 v85, s2, v97
	s_waitcnt vmcnt(3)
	ds_write_b128 v84, v[68:71]
	s_waitcnt vmcnt(2)
	ds_write_b128 v85, v[72:75] offset:8192
	s_sub_i32 s2, s8, 3
	s_and_b32 s2, s2, 7
	s_lshl_b32 s2, s2, 14
	v_add_u32_e32 v84, s2, v93
	v_add_u32_e32 v85, s2, v97
	s_waitcnt vmcnt(1)
	ds_write_b128 v84, v[76:79]
	s_waitcnt vmcnt(0)
	ds_write_b128 v85, v[80:83] offset:8192
	v_mov_b64_e32 v[6:7], v[2:3]
	v_mov_b64_e32 v[10:11], v[2:3]
	v_mov_b64_e32 v[14:15], v[2:3]
	v_mov_b64_e32 v[18:19], v[2:3]
	v_mov_b64_e32 v[22:23], v[2:3]
	v_mov_b64_e32 v[26:27], v[2:3]
	v_mov_b64_e32 v[30:31], v[2:3]
	v_mov_b64_e32 v[34:35], v[2:3]
	v_mov_b64_e32 v[4:5], v[0:1]
	v_mov_b64_e32 v[8:9], v[0:1]
	v_mov_b64_e32 v[12:13], v[0:1]
	v_mov_b64_e32 v[16:17], v[0:1]
	v_mov_b64_e32 v[20:21], v[0:1]
	v_mov_b64_e32 v[24:25], v[0:1]
	v_mov_b64_e32 v[28:29], v[0:1]
	v_mov_b64_e32 v[32:33], v[0:1]
	s_waitcnt lgkmcnt(0)
	s_barrier
.LBB0_411:
	v_sub_u32_e64 v0, v124, 4 clamp
	v_lshlrev_b32_e32 v0, 6, v0
	v_mad_u64_u32 v[2:3], s[2:3], v0, s48, v[98:99]
	v_lshl_add_u64 v[56:57], v[0:1], 1, v[100:101]
	global_load_dwordx4 v[52:55], v[2:3], off offset:1536
	s_nop 0
	global_load_dwordx4 v[56:59], v[56:57], off
	s_lshr_b32 s35, s31, 1
	s_sub_i32 s35, s35, s100
	s_and_b32 s35, s35, 7
	s_lshl_b32 s35, s35, 14
	v_or_b32_e32 v0, s35, v118
	v_or_b32_e32 v125, s35, v119
	v_mov_b32_e32 v126, v120
	s_mov_b32 s36, 0
	s_branch .LBB0_414

; __device__ __forceinline__ f32x4 mfma16(bf16x8 a, bf16x8 b, f32x4 c) { return __builtin_amdgcn_mfma_f32_16x16x32_bf16(a, b, c, 0, 0, 0); }
; __device__ __forceinline__ float ex2(float x) { return __builtin_amdgcn_exp2f(x); }
; __device__ __forceinline__ float lg2(float x) { return __builtin_amdgcn_logf(x); }
; __device__ __forceinline__ int otid() { int t = threadIdx.x; asm volatile("" : "+v"(t)); return t; }
; __device__ __forceinline__ void sb_group(const unsigned char* st, int kgp, int fo, const bf16x8 (&qf)[2][2], f32x4 (&o)[2][4], float (&R)[2],
;                                          float c2, int d0, bool masked) {
;     const int kg = (otid() & 63) >> 4;
;     bf16x8 kf[2][2], vf[4];
; #pragma unroll
;     for (int t = 0; t < 2; ++t)
; #pragma unroll
;         for (int c = 0; c < 2; ++c) kf[t][c] = lds_frag(st + ((kgp * 2 + t) * 2 + c) * 1024 + fo);
; #pragma unroll
;     for (int et = 0; et < 4; ++et) vf[et] = lds_frag(st + 8192 + (et * 2 + kgp) * 1024 + fo);
;     const f32x4 zero = {0.f, 0.f, 0.f, 0.f};
; #pragma unroll
;     for (int qt = 0; qt < 2; ++qt) {
;         const int dq = d0 + qt * 16;
;         f32x4 s[2];
; #pragma unroll
;         for (int t = 0; t < 2; ++t) s[t] = mfma16(kf[t][1], qf[1][qt], mfma16(kf[t][0], qf[0][qt], zero));
;         float lb[8], l1[8];
; #pragma unroll
;         for (int j = 0; j < 8; ++j) {
;             const float z2 = s[j >> 2][j & 3] * c2;
;             const float sp = lg2(1.f + ex2(-fabsf(z2)));
;             lb[j] = fminf(z2, 0.f) - sp;
;             l1[j] = lb[j] - z2;
;         }
; __device__ void attn_b_item(const Params& p, int layer, int b, int h, int qblk, unsigned char* smem) {
;     ...
;     for (int j = jmax; j >= 0; --j) {
;         attn_tile_load(tr, kbase, vbase, (j > 0 ? j - 1 : 0) * 64, tofs);
;         const unsigned char* st = smem + sidx * 16384;
; #pragma unroll 1
;     ...
;             const int g = j * 2 + kk;
;             if (g <= gmax && !done) {
;                 const int d0 = (qw0 + l15) - (g * 32 + kg * 8);
;                 sb_group(st, kk, fo, qf, o, R, c2, d0, g == gmax);
;                 done = __all(R[0] < RSTOP && R[1] < RSTOP);
.LBB0_414:
	s_add_i32 s101, s31, s36
	s_lshl_b32 s2, s100, 1
	s_sub_i32 s101, s101, s2
	s_cmp_lt_i32 s101, 0
	s_cbranch_scc0 .Lmy_b_ok
	s_mov_b64 s[24:25], exec
	s_branch .LBB0_413
.Lmy_b_ok:
	v_cmp_le_i32_e32 vcc, s101, v95
	s_xor_b64 s[2:3], s[22:23], -1
	s_andn2_b64 s[4:5], s[22:23], exec
	s_and_b64 s[6:7], s[22:23], exec
	s_and_b64 s[2:3], vcc, s[2:3]
	s_or_b64 s[22:23], s[4:5], s[6:7]
	s_and_saveexec_b64 s[24:25], s[2:3]
	s_cbranch_execz .LBB0_413
	v_mov_b32_e32 v127, v189
	ds_read_b128 v[88:91], v125
	ds_read_b128 v[84:87], v125 offset:1024
	ds_read_b128 v[80:83], v125 offset:2048
	ds_read_b128 v[76:79], v125 offset:3072
	ds_read_b128 v[72:75], v0
	ds_read_b128 v[68:71], v0 offset:2048
	ds_read_b128 v[64:67], v0 offset:4096
	ds_read_b128 v[60:63], v0 offset:6144
	s_waitcnt vmcnt(5) lgkmcnt(7)
	v_mfma_f32_16x16x32_bf16 v[102:105], v[88:91], v[36:39], 0
	v_cmp_eq_u32_e32 vcc, s101, v95
	s_waitcnt vmcnt(4) lgkmcnt(6)
	v_mfma_f32_16x16x32_bf16 v[108:111], v[84:87], v[40:43], v[102:105]
	s_waitcnt lgkmcnt(5)
	v_mfma_f32_16x16x32_bf16 v[102:105], v[80:83], v[36:39], 0
	s_waitcnt lgkmcnt(4)
	v_mfma_f32_16x16x32_bf16 v[112:115], v[76:79], v[40:43], v[102:105]
	s_nop 3
	v_mul_f32_e64 v2, v108, s60
	v_mul_f32_e64 v3, v109, s60
	v_exp_f32_e64 v102, -|v2|
	v_exp_f32_e64 v103, -|v3|
	v_min_f32_e32 v2, 0, v2
	v_min_f32_e32 v3, 0, v3
	v_add_f32_e32 v102, 1.0, v102
	v_add_f32_e32 v103, 1.0, v103
	v_log_f32_e32 v102, v102
	v_log_f32_e32 v103, v103
	s_nop 0
	v_pk_add_f32 v[2:3], v[2:3], v[102:103] neg_lo:[0,1] neg_hi:[0,1]
	v_pk_mul_f32 v[102:103], v[110:111], s[60:61] op_sel_hi:[1,0]
	v_pk_fma_f32 v[108:109], v[108:109], s[60:61], v[2:3] op_sel_hi:[1,0,1] neg_lo:[1,0,0] neg_hi:[1,0,0]
	v_exp_f32_e64 v104, -|v102|
	v_exp_f32_e64 v105, -|v103|
	v_min_f32_e32 v102, 0, v102
	v_min_f32_e32 v103, 0, v103
	v_add_f32_e32 v104, 1.0, v104
	v_add_f32_e32 v105, 1.0, v105
	v_log_f32_e32 v104, v104
	v_log_f32_e32 v105, v105
	s_nop 0
	v_pk_add_f32 v[102:103], v[102:103], v[104:105] neg_lo:[0,1] neg_hi:[0,1]
	v_pk_mul_f32 v[104:105], v[112:113], s[60:61] op_sel_hi:[1,0]
	v_pk_fma_f32 v[110:111], v[110:111], s[60:61], v[102:103] op_sel_hi:[1,0,1] neg_lo:[1,0,0] neg_hi:[1,0,0]
	v_exp_f32_e64 v106, -|v104|
	v_exp_f32_e64 v107, -|v105|
	v_min_f32_e32 v104, 0, v104
	v_min_f32_e32 v105, 0, v105
	v_add_f32_e32 v106, 1.0, v106
	v_add_f32_e32 v107, 1.0, v107
	v_log_f32_e32 v106, v106
	v_log_f32_e32 v107, v107
	s_nop 0
	v_pk_add_f32 v[104:105], v[104:105], v[106:107] neg_lo:[0,1] neg_hi:[0,1]
	v_pk_mul_f32 v[106:107], v[114:115], s[60:61] op_sel_hi:[1,0]
	v_pk_fma_f32 v[112:113], v[112:113], s[60:61], v[104:105] op_sel_hi:[1,0,1] neg_lo:[1,0,0] neg_hi:[1,0,0]
	v_exp_f32_e64 v128, -|v106|
	v_exp_f32_e64 v129, -|v107|
	v_min_f32_e32 v106, 0, v106
	v_min_f32_e32 v107, 0, v107
	v_add_f32_e32 v128, 1.0, v128
	v_add_f32_e32 v129, 1.0, v129
	v_log_f32_e32 v128, v128
	v_log_f32_e32 v129, v129
	s_nop 0
	v_pk_add_f32 v[106:107], v[106:107], v[128:129] neg_lo:[0,1] neg_hi:[0,1]
	s_nop 0
	v_pk_fma_f32 v[114:115], v[114:115], s[60:61], v[106:107] op_sel_hi:[1,0,1] neg_lo:[1,0,0] neg_hi:[1,0,0]
	s_and_saveexec_b64 s[18:19], vcc
	s_cbranch_execz .LBB0_417
	v_cmp_lt_i32_e64 s[14:15], 6, v126
	v_cmp_lt_i32_e64 s[16:17], 7, v126
	v_cmp_lt_i32_e64 s[12:13], 5, v126
	s_or_b64 s[14:15], s[16:17], s[14:15]
	v_cmp_lt_i32_e64 s[10:11], 4, v126
	s_or_b64 s[12:13], s[14:15], s[12:13]
	v_cmp_lt_i32_e64 s[8:9], 3, v126
	s_or_b64 s[10:11], s[12:13], s[10:11]
	v_cmp_lt_i32_e64 s[6:7], 2, v126
	s_or_b64 s[8:9], s[10:11], s[8:9]
	v_cmp_lt_i32_e64 s[4:5], 1, v126
	s_or_b64 s[6:7], s[8:9], s[6:7]
	v_cmp_lt_i32_e64 s[2:3], 0, v126
	s_or_b64 s[4:5], s[6:7], s[4:5]
	s_or_b64 s[2:3], s[4:5], s[2:3]
	v_cndmask_b32_e64 v107, v211, v107, s[16:17]
	v_cndmask_b32_e64 v106, v211, v106, s[14:15]
	v_cndmask_b32_e64 v105, v211, v105, s[12:13]
	v_cndmask_b32_e64 v104, v211, v104, s[10:11]
	v_cndmask_b32_e64 v103, v211, v103, s[8:9]
	v_cndmask_b32_e64 v102, v211, v102, s[6:7]
	v_cndmask_b32_e64 v3, v211, v3, s[4:5]
	v_cndmask_b32_e64 v2, v211, v2, s[2:3]
	v_cndmask_b32_e64 v108, 0, v108, s[2:3]
	v_cndmask_b32_e64 v109, 0, v109, s[4:5]
	v_cndmask_b32_e64 v110, 0, v110, s[6:7]
	v_cndmask_b32_e64 v111, 0, v111, s[8:9]
	v_cndmask_b32_e64 v112, 0, v112, s[10:11]
	v_cndmask_b32_e64 v113, 0, v113, s[12:13]
	v_cndmask_b32_e64 v114, 0, v114, s[14:15]
	v_cndmask_b32_e64 v115, 0, v115, s[16:17]

; __device__ void attn_b_item(const Params& p, int layer, int b, int h, int qblk, unsigned char* smem) {
;     ...
;         if (j > 0) attn_tile_store(tr, smem + (sidx ^ 1) * 16384, tofs);
;         sidx ^= 1;
;         if (block_all(done, smem, j & 1)) break;
.LBB0_419:
	v_subrev_co_u32_e32 v0, vcc, 1, v124
	s_lshr_b32 s2, s31, 1
	s_cmp_lt_i32 s2, 4
	s_cbranch_scc1 .LBB0_421
	s_add_i32 s2, s2, 4
	s_and_b32 s2, s2, 7
	s_lshl_b32 s2, s2, 14
	v_add_u32_e32 v3, s2, v93
	v_add_u32_e32 v2, s2, v97
	s_waitcnt vmcnt(1)
	ds_write_b128 v3, v[52:55]
	s_waitcnt vmcnt(0)
	ds_write_b128 v2, v[56:59] offset:8192

; __global__ void __launch_bounds__(NTHREADS, 2) fwd_kernel(Params p) {
;     __shared__ __attribute__((aligned(1024))) unsigned char smem[131072 + 1024];
	.amdhsa_kernel _Z10fwd_kernel6Params
		.amdhsa_group_segment_fixed_size 132096
		.amdhsa_private_segment_fixed_size 0
		.amdhsa_kernarg_size 440
		.amdhsa_user_sgpr_count 2
		.amdhsa_user_sgpr_dispatch_ptr 0
		.amdhsa_user_sgpr_queue_ptr 0
		.amdhsa_user_sgpr_kernarg_segment_ptr 1
		.amdhsa_user_sgpr_dispatch_id 0
		.amdhsa_user_sgpr_kernarg_preload_length 0
		.amdhsa_user_sgpr_kernarg_preload_offset 0
		.amdhsa_user_sgpr_private_segment_size 0
		.amdhsa_uses_dynamic_stack 0
		.amdhsa_enable_private_segment 0
		.amdhsa_system_sgpr_workgroup_id_x 1
		.amdhsa_system_sgpr_workgroup_id_y 0
		.amdhsa_system_sgpr_workgroup_id_z 0
		.amdhsa_system_sgpr_workgroup_info 0
		.amdhsa_system_vgpr_workitem_id 2
		.amdhsa_next_free_vgpr 256
		.amdhsa_next_free_sgpr 102
		.amdhsa_accum_offset 256
		.amdhsa_reserve_vcc 1
		.amdhsa_float_round_mode_32 0
		.amdhsa_float_round_mode_16_64 0
		.amdhsa_float_denorm_mode_32 3
		.amdhsa_float_denorm_mode_16_64 3
		.amdhsa_dx10_clamp 1
		.amdhsa_ieee_mode 1
		.amdhsa_fp16_overflow 0
		.amdhsa_tg_split 0
		.amdhsa_exception_fp_ieee_invalid_op 0
		.amdhsa_exception_fp_denorm_src 0
		.amdhsa_exception_fp_ieee_div_zero 0
		.amdhsa_exception_fp_ieee_overflow 0
		.amdhsa_exception_fp_ieee_underflow 0
		.amdhsa_exception_fp_ieee_inexact 0
		.amdhsa_exception_int_div_zero 0
	.end_amdhsa_kernel

; __global__ void __launch_bounds__(NTHREADS, 2) fwd_kernel(Params p) {
;     __shared__ __attribute__((aligned(1024))) unsigned char smem[131072 + 1024];
amdhsa.kernels:
  - .agpr_count:     0
    .args:
      - .offset:         0
        .size:           184
        .value_kind:     by_value
      - .offset:         184
        .size:           4
        .value_kind:     hidden_block_count_x
      - .offset:         188
        .size:           4
        .value_kind:     hidden_block_count_y
      - .offset:         192
        .size:           4
        .value_kind:     hidden_block_count_z
      - .offset:         196
        .size:           2
        .value_kind:     hidden_group_size_x
      - .offset:         198
        .size:           2
        .value_kind:     hidden_group_size_y
      - .offset:         200
        .size:           2
        .value_kind:     hidden_group_size_z
      - .offset:         202
        .size:           2
        .value_kind:     hidden_remainder_x
      - .offset:         204
        .size:           2
        .value_kind:     hidden_remainder_y
      - .offset:         206
        .size:           2
        .value_kind:     hidden_remainder_z
      - .offset:         224
        .size:           8
        .value_kind:     hidden_global_offset_x
      - .offset:         232
        .size:           8
        .value_kind:     hidden_global_offset_y
      - .offset:         240
        .size:           8
        .value_kind:     hidden_global_offset_z
      - .offset:         248
        .size:           2
        .value_kind:     hidden_grid_dims
      - .offset:         272
        .size:           8
        .value_kind:     hidden_multigrid_sync_arg
    .group_segment_fixed_size: 132096
    .kernarg_segment_align: 8
    .kernarg_segment_size: 440
    .language:       OpenCL C
    .language_version:
      - 2
      - 0
    .max_flat_workgroup_size: 512
    .name:           _Z10fwd_kernel6Params
    .private_segment_fixed_size: 0
    .sgpr_count:     108
    .sgpr_spill_count: 66
    .symbol:         _Z10fwd_kernel6Params.kd
    .uniform_work_group_size: 1
    .uses_dynamic_stack: false
    .vgpr_count:     256
    .vgpr_spill_count: 0
    .wavefront_size: 64
